# out-proj epilogue row-scale loads batched; first grid seam uses the two-level barrier; SSD next-step C/B tile fill moved mid-step behind an extra barrier
# speedup vs baseline: 1.0094x; 1.0054x over previous
; #define LAS __attribute__((address_space(3)))
; __device__ __forceinline__ unsigned xb_add(unsigned* p, unsigned v) { return __hip_atomic_fetch_add(p, v, __ATOMIC_RELAXED, __HIP_MEMORY_SCOPE_AGENT); }
; __device__ __forceinline__ unsigned xb_xcc_id() { return (unsigned)__builtin_amdgcn_s_getreg((3 << 11) | 20) & 0xFu; }
; __device__ __forceinline__ void xcd_barrier(const XcdBarrier& b) {
;     asm volatile("s_waitcnt vmcnt(0)" ::: "memory");
;     __syncthreads();
;     if (threadIdx.x == 0) {
;         unsigned* bar = b.bar;
;         __builtin_amdgcn_s_waitcnt(0);
;         unsigned nloc = b.st[0], nx = b.st[1];
;         if (nloc == 0u) { xcd_barrier_complete(bar, b.x, nloc, nx); b.st[0] = nloc; b.st[1] = nx; }
;         const unsigned old = xb_add(&bar[XB_XSUB(b.x)], 1u);
; __global__ void __launch_bounds__(512, 2) mk_fwd(Args a) {
;     ...
;         if (!first) { if (nsync == 0) grid.sync(); else { XcdBarrier xb; xb.bar = (unsigned*)(a.ws + WS_BAR); xb.x = xb_xcc_id(); xb.st = (volatile LAS unsigned*)(lds + LDS_BAR_OFF); xcd_barrier(xb); } ++nsync; }
.LBB0_8:
	s_and_b64 vcc, exec, s[4:5]
	s_cbranch_vccnz .LBB0_76
	s_getreg_b32 s3, hwreg(HW_REG_XCC_ID, 0, 4)
	s_waitcnt vmcnt(0)
	s_barrier
	s_mov_b64 s[0:1], exec
	v_readlane_b32 s4, v253, 11
	v_readlane_b32 s5, v253, 12
	s_and_b64 s[4:5], s[0:1], s[4:5]
	s_mov_b64 exec, s[4:5]
	s_cbranch_execz .LBB0_63
	v_readlane_b32 s4, v253, 41
	s_waitcnt vmcnt(0) expcnt(0) lgkmcnt(0)
	s_and_b32 s3, s3, 15
	v_mov_b32_e32 v0, s4
	ds_read_b32 v2, v0
	v_readlane_b32 s4, v253, 42
	s_waitcnt lgkmcnt(0)
	v_cmp_ne_u32_e32 vcc, 0, v2
	v_mov_b32_e32 v0, s4
	ds_read_b32 v0, v0
	s_cbranch_vccnz .LBB0_27
	s_mov_b32 s10, 1
	s_branch .LBB0_14

; #define LAS __attribute__((address_space(3)))
; #define INP(k) inp_(a.in[k])
; __device__ __forceinline__ void phase_C1(const Args& a, unsigned char* ws, const int bid, int l, LAS unsigned char* lds, int tid, int wave, int lane) {
;     ...
;         const float Acoef = -__expf(INP(12)[l * 64 + dir * 32 + h]);
;         const float dskip = INP(13)[l * 32 + h];
;         f32x4 Hacc[4];
; #pragma unroll
;         for (int j = 0; j < 4; ++j) Hacc[j] = (f32x4){0.f, 0.f, 0.f, 0.f};
;         for (int i = tid; i < 17408 / 4; i += 512) ((LAS unsigned*)L_H)[i] = 0u;
;         u32x4 pc[4], pb[4], px[2]; float pd0 = 0.f, pd1 = 0.f;
;     ...
;         SSD_ISSUE(0);
; #pragma unroll 1
;         for (int step = 0; step < 66; ++step) {
;             const int row0 = SSD_GC(step) * 128;
; #pragma unroll
;             for (int i = 0; i < 4; ++i) { *(LAS u32x4*)(L_C + wCB + i * 32 * 272) = pc[i]; *(LAS u32x4*)(L_B + wCB + i * 32 * 272) = pb[i]; }
.LBB0_95:
	s_cmp_lg_u32 s4, 0
	s_cselect_b64 s[70:71], -1, 0
	s_lshl_b32 s5, s46, 6
	s_add_i32 s0, s5, 0x49
	v_writelane_b32 v255, s0, 55
	s_lshl_b32 s94, s46, 1
	s_or_b32 s0, s5, 6
	s_or_b32 s3, s94, 1
	v_writelane_b32 v255, s0, 56
	s_lshl_b32 s0, s45, 2
	v_readlane_b32 s42, v254, 62
	v_readlane_b32 s43, v254, 63
	s_add_u32 s0, s42, s0
	s_addc_u32 s38, s43, 0
	s_lshl_b32 s42, s44, 2
	s_add_u32 s88, s0, s42
	s_addc_u32 s89, s38, 0
	s_lshl_b32 s0, s4, 12
	v_readlane_b32 s38, v254, 60
	s_add_u32 s0, s38, s0
	v_readlane_b32 s38, v254, 61
	s_addc_u32 s43, s38, 0
	s_lshl_b32 s38, s47, 1
	s_add_u32 s42, s0, s38
	s_addc_u32 s43, s43, 0
	v_lshl_add_u64 v[114:115], s[42:43], 0, v[160:161]
	v_readlane_b32 s42, v255, 8
	s_waitcnt vmcnt(11)
	v_mul_f32_e32 v41, 0x3fb8aa3b, v41
	v_readlane_b32 s43, v255, 9
	v_exp_f32_e32 v166, v41
	s_cmp_eq_u32 s4, 0
	v_cndmask_b32_e64 v41, 0, 1, s[42:43]
	v_readlane_b32 s42, v255, 6
	v_readlane_b32 s43, v255, 7
	v_readlane_b32 s44, v255, 12
	v_readlane_b32 s45, v255, 13
	v_cndmask_b32_e64 v42, 0, 1, s[42:43]
	s_cselect_b64 s[42:43], -1, 0
	v_cndmask_b32_e64 v41, v41, v42, s[42:43]
	v_cndmask_b32_e64 v42, 0, 1, s[44:45]
	v_readlane_b32 s44, v255, 10
	v_readlane_b32 s45, v255, 11
	v_and_b32_e32 v41, 1, v41
	v_readlane_b32 s60, v255, 38
	v_cndmask_b32_e64 v43, 0, 1, s[44:45]
	v_readlane_b32 s44, v255, 16
	v_readlane_b32 s45, v255, 17
	v_cndmask_b32_e64 v42, v42, v43, s[42:43]
	v_readlane_b32 s61, v255, 39
	v_cndmask_b32_e64 v43, 0, 1, s[44:45]
	v_readlane_b32 s44, v255, 14
	v_readlane_b32 s45, v255, 15
	v_readlane_b32 s62, v255, 42
	v_readlane_b32 s63, v255, 43
	v_cndmask_b32_e64 v44, 0, 1, s[44:45]
	v_readlane_b32 s44, v255, 20
	v_readlane_b32 s45, v255, 21
	v_cndmask_b32_e64 v43, v43, v44, s[42:43]
	v_readlane_b32 s64, v255, 46
	v_cndmask_b32_e64 v44, 0, 1, s[44:45]
	v_readlane_b32 s44, v255, 18
	v_readlane_b32 s45, v255, 19
	v_readlane_b32 s65, v255, 47
	v_readlane_b32 s66, v255, 50
	v_cndmask_b32_e64 v45, 0, 1, s[44:45]
	v_readlane_b32 s44, v255, 24
	v_readlane_b32 s45, v255, 25
	v_cndmask_b32_e64 v44, v44, v45, s[42:43]
	v_readlane_b32 s67, v255, 51
	v_cndmask_b32_e64 v45, 0, 1, s[44:45]
	v_readlane_b32 s44, v255, 22
	v_readlane_b32 s45, v255, 23
	s_mov_b32 s74, 0
	s_waitcnt vmcnt(10)
	v_mov_b32_e32 v111, v110
	v_cndmask_b32_e64 v46, 0, 1, s[44:45]
	v_readlane_b32 s44, v255, 28
	v_readlane_b32 s45, v255, 29
	v_cndmask_b32_e64 v45, v45, v46, s[42:43]
	s_movk_i32 s4, 0x48
	v_cndmask_b32_e64 v46, 0, 1, s[44:45]
	v_readlane_b32 s44, v255, 26
	v_readlane_b32 s45, v255, 27
	s_lshl_b32 s95, s1, 1
	s_mov_b32 s72, 0
	v_cndmask_b32_e64 v47, 0, 1, s[44:45]
	v_readlane_b32 s44, v255, 32
	v_readlane_b32 s45, v255, 33
	v_cndmask_b32_e64 v46, v46, v47, s[42:43]
	v_mov_b32_e32 v50, v40
	v_cndmask_b32_e64 v47, 0, 1, s[44:45]
	v_readlane_b32 s44, v255, 30
	v_readlane_b32 s45, v255, 31
	v_mov_b32_e32 v51, v40
	v_mov_b32_e32 v52, v40
	v_cndmask_b32_e64 v48, 0, 1, s[44:45]
	v_readlane_b32 s44, v255, 36
	v_readlane_b32 s45, v255, 37
	v_cndmask_b32_e64 v47, v47, v48, s[42:43]
	v_mov_b32_e32 v53, v40
	v_cndmask_b32_e64 v48, 0, 1, s[44:45]
	v_readlane_b32 s44, v255, 34
	v_readlane_b32 s45, v255, 35
	v_mov_b32_e32 v54, v40
	v_mov_b32_e32 v55, v40
	v_cndmask_b32_e64 v49, 0, 1, s[44:45]
	v_cmp_eq_u32_e64 s[44:45], 1, v41
	v_and_b32_e32 v41, 1, v42
	v_cmp_eq_u32_e64 s[46:47], 1, v41
	v_and_b32_e32 v41, 1, v43
	v_cmp_eq_u32_e64 s[48:49], 1, v41
	v_and_b32_e32 v41, 1, v44
	v_cmp_eq_u32_e64 s[50:51], 1, v41
	v_and_b32_e32 v41, 1, v45
	v_cmp_eq_u32_e64 s[52:53], 1, v41
	v_and_b32_e32 v41, 1, v46
	v_cndmask_b32_e64 v48, v48, v49, s[42:43]
	v_cmp_eq_u32_e64 s[54:55], 1, v41
	v_and_b32_e32 v41, 1, v47
	v_cmp_eq_u32_e64 s[56:57], 1, v41
	v_and_b32_e32 v41, 1, v48
	v_cmp_eq_u32_e64 s[58:59], 1, v41
	v_cndmask_b32_e64 v41, 0, 1, s[60:61]
	v_readlane_b32 s60, v255, 40
	v_readlane_b32 s61, v255, 41
	v_mov_b32_e32 v43, v40
	v_mov_b32_e32 v44, v40
	v_cndmask_b32_e64 v42, 0, 1, s[60:61]
	v_cndmask_b32_e64 v41, v42, v41, s[42:43]
	v_and_b32_e32 v41, 1, v41
	v_cmp_eq_u32_e64 s[60:61], 1, v41
	v_cndmask_b32_e64 v41, 0, 1, s[62:63]
	v_readlane_b32 s62, v255, 44
	v_readlane_b32 s63, v255, 45
	v_mov_b32_e32 v45, v40
	v_mov_b32_e32 v46, v40
	v_cndmask_b32_e64 v42, 0, 1, s[62:63]
	v_cndmask_b32_e64 v41, v42, v41, s[42:43]
	v_and_b32_e32 v41, 1, v41
	v_cmp_eq_u32_e64 s[62:63], 1, v41
	v_cndmask_b32_e64 v41, 0, 1, s[64:65]
	v_readlane_b32 s64, v255, 48
	v_readlane_b32 s65, v255, 49
	v_mov_b32_e32 v47, v40
	v_mov_b32_e32 v48, v40
	v_cndmask_b32_e64 v42, 0, 1, s[64:65]
	v_cndmask_b32_e64 v41, v42, v41, s[42:43]
	v_and_b32_e32 v41, 1, v41
	v_cmp_eq_u32_e64 s[64:65], 1, v41
	v_cndmask_b32_e64 v41, 0, 1, s[66:67]
	v_readlane_b32 s66, v255, 52
	v_readlane_b32 s67, v255, 53
	v_mov_b32_e32 v49, v40
	s_nop 0
	v_cndmask_b32_e64 v42, 0, 1, s[66:67]
	v_cndmask_b32_e64 v41, v42, v41, s[42:43]
	v_and_b32_e32 v41, 1, v41
	v_cmp_eq_u32_e64 s[66:67], 1, v41
	v_mov_b32_e32 v41, v40
	v_mov_b32_e32 v42, v40
	s_waitcnt vmcnt(0)
	ds_write_b128 v144, v[0:3]
	ds_write_b128 v144, v[4:7] offset:34816
	ds_write_b128 v144, v[8:11] offset:8704
	ds_write_b128 v144, v[12:15] offset:43520
	ds_write_b128 v144, v[16:19] offset:17408
	ds_write_b128 v144, v[20:23] offset:52224
	ds_write_b128 v144, v[24:27] offset:26112
	ds_write_b128 v144, v[28:31] offset:60928
	s_branch .LBB0_97

; #define LAS __attribute__((address_space(3)))
; __device__ __forceinline__ void phase_C1(const Args& a, unsigned char* ws, const int bid, int l, LAS unsigned char* lds, int tid, int wave, int lane) {
;     ...
; #pragma unroll
;             for (int i = 0; i < 2; ++i) *(LAS u32x4*)(L_X + wX + i * 64 * 144) = px[i];
.Lssd_ladder:
	s_waitcnt vmcnt(3)
	ds_write_b128 v145, v[32:35]
	s_waitcnt vmcnt(2)
	ds_write_b128 v145, v[36:39] offset:9216

; #define LAS __attribute__((address_space(3)))
; __device__ __forceinline__ unsigned cvt_pk_bf16(float lo, float hi) { unsigned r; asm volatile("v_cvt_pk_bf16_f32 %0, %1, %2" : "=v"(r) : "v"(lo), "v"(hi)); return r; }
; __device__ __forceinline__ void phase_C1(const Args& a, unsigned char* ws, const int bid, int l, LAS unsigned char* lds, int tid, int wave, int lane) {
;     ...
; #pragma unroll
;             for (int i = 0; i < 4; ++i) { *(LAS u32x4*)(L_C + wCB + i * 32 * 272) = pc[i]; *(LAS u32x4*)(L_B + wCB + i * 32 * 272) = pb[i]; }
;     ...
;             { const int q = qt * 16 + fr; const float csq = cs[q], eq = ecs[q];
;               f32x4 gd = accA[0];
; #pragma unroll
;               for (int kt = 1; kt < 8; ++kt) { const bool is = (kt == qt); gd.x = is ? accA[kt].x : gd.x; gd.y = is ? accA[kt].y : gd.y; gd.z = is ? accA[kt].z : gd.z; gd.w = is ? accA[kt].w : gd.w; }
; #pragma unroll
;               for (int kt = 0; kt < 8; ++kt) { const int k0 = kt * 16 + fq * 4;
;                   const bool kept = dir == 0 ? (kt < qt) : (kt > qt);
;                   const float f1 = __expf(csq - refarr[kt]); const f32x4 f2 = *(const LAS f32x4*)(f2dt + k0);
;                   float m[4];
; #pragma unroll
;                   for (int r = 0; r < 4; ++r) m[r] = kept ? accA[kt][r] * f1 * f2[r] : 0.f;
;                   u32x2 o; o.x = cvt_pk_bf16(m[0], m[1]); o.y = cvt_pk_bf16(m[2], m[3]);
;                   *(LAS u32x2*)(L_M + q * 272 + k0 * 2) = o; }
.Lssd_m_section:
	ds_read_b32 v117, v127
	ds_read_b32 v116, v128
	ds_read_b128 v[180:183], v130
	ds_read_b128 v[184:187], v131
	s_waitcnt lgkmcnt(0)
	s_barrier
	s_cmp_eq_u32 s4, 7
	s_cbranch_scc1 .Lssd_nofill
	s_waitcnt vmcnt(9)
	ds_write_b128 v144, v[0:3]
	s_waitcnt vmcnt(8)
	ds_write_b128 v144, v[4:7] offset:34816
	s_waitcnt vmcnt(7)
	ds_write_b128 v144, v[8:11] offset:8704
	s_waitcnt vmcnt(6)
	ds_write_b128 v144, v[12:15] offset:43520
	s_waitcnt vmcnt(5)
	ds_write_b128 v144, v[16:19] offset:17408
	s_waitcnt vmcnt(4)
	ds_write_b128 v144, v[20:23] offset:52224
	s_waitcnt vmcnt(3)
	ds_write_b128 v144, v[24:27] offset:26112
	s_waitcnt vmcnt(2)
	ds_write_b128 v144, v[28:31] offset:60928
.Lssd_nofill:
	v_cndmask_b32_e64 v169, v102, v98, s[10:11]
	v_cndmask_b32_e64 v170, v101, v97, s[10:11]
	v_cndmask_b32_e64 v171, v100, v96, s[10:11]
	v_cndmask_b32_e64 v168, v103, v99, s[10:11]
	v_sub_f32_e32 v172, v117, v244
	v_mul_f32_e32 v172, 0x3fb8aa3b, v172
	v_exp_f32_e32 v176, v172
	s_nop 0
	v_readlane_b32 s0, v253, 52
	v_mul_f32_e32 v100, v100, v176
	v_mul_f32_e32 v101, v101, v176
	v_mul_f32_e32 v102, v102, v176
	v_mul_f32_e32 v100, v212, v100
	v_mul_f32_e32 v101, v213, v101
	v_mul_f32_e32 v102, v214, v102
	v_mul_f32_e32 v103, v103, v176
	v_cndmask_b32_e64 v100, 0, v100, s[44:45]
	v_cndmask_b32_e64 v101, 0, v101, s[44:45]
	v_cndmask_b32_e64 v102, 0, v102, s[44:45]
	v_mul_f32_e32 v103, v215, v103
	v_cndmask_b32_e64 v103, 0, v103, s[44:45]
	v_cvt_pk_bf16_f32 v100, v100, v101
	v_cvt_pk_bf16_f32 v101, v102, v103
	v_add_u32_e32 v102, v129, v108
	ds_write_b64 v102, v[100:101]
	v_readlane_b32 s0, v253, 53
	v_sub_f32_e32 v100, v117, v245
	v_mul_f32_e32 v100, 0x3fb8aa3b, v100
	v_exp_f32_e32 v172, v100
	s_nop 0
	v_mul_f32_e32 v96, v96, v172
	v_mul_f32_e32 v97, v97, v172
	v_mul_f32_e32 v96, v216, v96
	v_cndmask_b32_e64 v96, 0, v96, s[46:47]
	v_mul_f32_e32 v97, v217, v97
	v_mul_f32_e32 v98, v98, v172
	v_mul_f32_e32 v99, v99, v172
	v_cndmask_b32_e64 v97, 0, v97, s[46:47]
	v_mul_f32_e32 v98, v218, v98
	v_mul_f32_e32 v99, v219, v99
	v_cvt_pk_bf16_f32 v96, v96, v97
	v_cndmask_b32_e64 v98, 0, v98, s[46:47]
	v_cndmask_b32_e64 v99, 0, v99, s[46:47]
	v_cvt_pk_bf16_f32 v97, v98, v99
	ds_write_b64 v148, v[96:97]
	v_readlane_b32 s0, v253, 54
	v_mov_b32_e32 v172, 0
	v_sub_f32_e32 v96, v117, v246
	v_mul_f32_e32 v96, 0x3fb8aa3b, v96
	v_exp_f32_e32 v100, v96
	s_nop 0
	v_mul_f32_e32 v101, v88, v100
	v_mul_f32_e32 v96, v220, v101
	v_mul_f32_e32 v101, v89, v100
	v_cndmask_b32_e64 v96, 0, v96, s[48:49]
	v_mul_f32_e32 v97, v221, v101
	v_mul_f32_e32 v101, v90, v100
	v_mul_f32_e32 v100, v91, v100
	v_cndmask_b32_e64 v97, 0, v97, s[48:49]
	v_mul_f32_e32 v98, v222, v101
	v_mul_f32_e32 v99, v223, v100
	v_cvt_pk_bf16_f32 v96, v96, v97
	v_cndmask_b32_e64 v98, 0, v98, s[48:49]
	v_cndmask_b32_e64 v99, 0, v99, s[48:49]
	v_cvt_pk_bf16_f32 v97, v98, v99
	ds_write_b64 v149, v[96:97]
	v_readlane_b32 s0, v253, 55
	v_sub_f32_e32 v96, v117, v247
	v_mul_f32_e32 v96, 0x3fb8aa3b, v96
	v_exp_f32_e32 v100, v96
	s_nop 0
	v_mul_f32_e32 v101, v80, v100
	v_mul_f32_e32 v96, v224, v101
	v_mul_f32_e32 v101, v81, v100
	v_cndmask_b32_e64 v96, 0, v96, s[50:51]
	v_mul_f32_e32 v97, v225, v101
	v_mul_f32_e32 v101, v82, v100
	v_mul_f32_e32 v100, v83, v100
	v_cndmask_b32_e64 v97, 0, v97, s[50:51]
	v_mul_f32_e32 v98, v226, v101
	v_mul_f32_e32 v99, v227, v100
	v_cvt_pk_bf16_f32 v96, v96, v97
	v_cndmask_b32_e64 v98, 0, v98, s[50:51]
	v_cndmask_b32_e64 v99, 0, v99, s[50:51]
	v_cvt_pk_bf16_f32 v97, v98, v99
	ds_write_b64 v150, v[96:97]
	v_readlane_b32 s0, v253, 56
	v_sub_f32_e32 v96, v117, v248
	v_mul_f32_e32 v96, 0x3fb8aa3b, v96
	v_exp_f32_e32 v100, v96
	s_nop 0
	v_mul_f32_e32 v101, v92, v100
	v_mul_f32_e32 v96, v228, v101
	v_mul_f32_e32 v101, v93, v100
	v_cndmask_b32_e64 v96, 0, v96, s[52:53]
	v_mul_f32_e32 v97, v229, v101
	v_mul_f32_e32 v101, v94, v100
	v_mul_f32_e32 v100, v95, v100
	v_cndmask_b32_e64 v97, 0, v97, s[52:53]
	v_mul_f32_e32 v98, v230, v101
	v_mul_f32_e32 v99, v231, v100
	v_cvt_pk_bf16_f32 v96, v96, v97
	v_cndmask_b32_e64 v98, 0, v98, s[52:53]
	v_cndmask_b32_e64 v99, 0, v99, s[52:53]
	v_cvt_pk_bf16_f32 v97, v98, v99
	ds_write_b64 v151, v[96:97]
	v_readlane_b32 s0, v253, 57
	v_sub_f32_e32 v96, v117, v249
	v_mul_f32_e32 v96, 0x3fb8aa3b, v96
	v_exp_f32_e32 v100, v96
	s_nop 0
	v_mul_f32_e32 v101, v84, v100
	v_mul_f32_e32 v96, v232, v101
	v_mul_f32_e32 v101, v85, v100
	v_cndmask_b32_e64 v96, 0, v96, s[54:55]
	v_mul_f32_e32 v97, v233, v101
	v_mul_f32_e32 v101, v86, v100
	v_mul_f32_e32 v100, v87, v100
	v_cndmask_b32_e64 v97, 0, v97, s[54:55]
	v_mul_f32_e32 v98, v234, v101
	v_mul_f32_e32 v99, v235, v100
	v_cvt_pk_bf16_f32 v96, v96, v97
	v_cndmask_b32_e64 v98, 0, v98, s[54:55]
	v_cndmask_b32_e64 v99, 0, v99, s[54:55]
	v_cvt_pk_bf16_f32 v97, v98, v99
	ds_write_b64 v152, v[96:97]
	v_readlane_b32 s0, v253, 58
	v_sub_f32_e32 v96, v117, v250
	v_mul_f32_e32 v96, 0x3fb8aa3b, v96
	v_exp_f32_e32 v100, v96
	s_nop 0
	v_mul_f32_e32 v101, v76, v100
	v_mul_f32_e32 v96, v236, v101
	v_mul_f32_e32 v101, v77, v100
	v_cndmask_b32_e64 v96, 0, v96, s[56:57]
	v_mul_f32_e32 v97, v237, v101
	v_mul_f32_e32 v101, v78, v100
	v_mul_f32_e32 v100, v79, v100
	v_cndmask_b32_e64 v97, 0, v97, s[56:57]
	v_mul_f32_e32 v98, v238, v101
	v_mul_f32_e32 v99, v239, v100
	v_cvt_pk_bf16_f32 v96, v96, v97
	v_cndmask_b32_e64 v98, 0, v98, s[56:57]
	v_cndmask_b32_e64 v99, 0, v99, s[56:57]
	v_cvt_pk_bf16_f32 v97, v98, v99
	ds_write_b64 v153, v[96:97]
	v_sub_f32_e32 v96, v117, v251
	v_mul_f32_e32 v96, 0x3fb8aa3b, v96
	v_exp_f32_e32 v100, v96
	s_nop 0
	v_mul_f32_e32 v101, v72, v100
	v_mul_f32_e32 v96, v240, v101
	v_mul_f32_e32 v101, v73, v100
	v_mul_f32_e32 v97, v241, v101
	v_mul_f32_e32 v101, v74, v100
	v_mul_f32_e32 v100, v75, v100
	v_cndmask_b32_e64 v96, 0, v96, s[58:59]
	v_cndmask_b32_e64 v97, 0, v97, s[58:59]
	v_mul_f32_e32 v98, v242, v101
	v_mul_f32_e32 v99, v243, v100
	v_cndmask_b32_e64 v98, 0, v98, s[58:59]
	v_cndmask_b32_e64 v99, 0, v99, s[58:59]
	v_cvt_pk_bf16_f32 v96, v96, v97
	v_cvt_pk_bf16_f32 v97, v98, v99
	ds_write_b64 v154, v[96:97]
	s_and_saveexec_b64 s[0:1], s[60:61]
	s_cbranch_execz .LBB0_123
	v_cndmask_b32_e64 v88, v171, v88, s[12:13]
	v_cndmask_b32_e64 v80, v88, v80, s[14:15]
	v_sub_f32_e32 v88, v117, v180
	v_mul_f32_e32 v88, 0x3fb8aa3b, v88
	v_cndmask_b32_e64 v80, v80, v92, s[16:17]
	v_exp_f32_e32 v88, v88
	v_cndmask_b32_e64 v80, v80, v84, s[18:19]
	v_cndmask_b32_e64 v76, v80, v76, s[20:21]
	v_cndmask_b32_e64 v72, v76, v72, s[22:23]
	v_mul_f32_e32 v72, v72, v88
	v_mul_f32_e32 v172, v184, v72
; #define LAS __attribute__((address_space(3)))
; __device__ __forceinline__ void phase_C1(const Args& a, unsigned char* ws, const int bid, int l, LAS unsigned char* lds, int tid, int wave, int lane) {
;     ...
;               { const int k0 = qt * 16 + fq * 4; const f32x4 ck = *(const LAS f32x4*)(cs + k0), dk = *(const LAS f32x4*)(dtv + k0); float m[4];
; #pragma unroll
;                 for (int r = 0; r < 4; ++r) { const int kk = k0 + r; const bool keep = dir == 0 ? (kk <= q) : (kk >= q); m[r] = keep ? gd[r] * __expf(csq - ck[r]) * dk[r] : 0.f; }
;                 u32x2 o; o.x = cvt_pk_bf16(m[0], m[1]); o.y = cvt_pk_bf16(m[2], m[3]);
;                 *(LAS u32x2*)(L_M + q * 272 + k0 * 2) = o; }
;               f32x4 accB[4];
; #pragma unroll
;               for (int j = 0; j < 4; ++j) accB[j] = (f32x4){0.f, 0.f, 0.f, 0.f};
; #pragma unroll
;               for (int s = 0; s < 4; ++s) { const bf16x8 mq = *(const LAS bf16x8*)(L_M + qt * (16 * 272) + rb + s * 64);
;                   s16x4 xlo[4], xhi[4];
; #pragma unroll
;                   for (int pt = 0; pt < 4; ++pt) { xlo[pt] = __builtin_amdgcn_ds_read_tr16_b64_v4i16((LAS s16x4*)(L_X + trXp + (32 * s) * 144 + (32 * (pt >> 1) + 4 * (pt & 1)) * 2));
;                       xhi[pt] = __builtin_amdgcn_ds_read_tr16_b64_v4i16((LAS s16x4*)(L_X + trXp + (32 * s + 4) * 144 + (32 * (pt >> 1) + 4 * (pt & 1)) * 2)); }
;                   __builtin_amdgcn_sched_barrier(0);
; #pragma unroll
;                   for (int pt = 0; pt < 4; ++pt) { const bf16x8 xf = (bf16x8){xlo[pt].x, xlo[pt].y, xlo[pt].z, xlo[pt].w, xhi[pt].x, xhi[pt].y, xhi[pt].z, xhi[pt].w}; accB[pt] = MFMA16(xf, mq, accB[pt]); }
;                   __builtin_amdgcn_sched_barrier(0); }
;               bf16_t* yrow = z + (size_t)(row0 + q) * ZW + dir * 2048 + h * 64 + 8 * fq;
; #pragma unroll
;               for (int m = 0; m < 2; ++m) { float y[8];
; #pragma unroll
;                   for (int r = 0; r < 4; ++r) { y[r] = accB[2 * m][r] + eq * accC[2 * m][r]; y[4 + r] = accB[2 * m + 1][r] + eq * accC[2 * m + 1][r]; }
;                   if (dir == 0) { const u32x4 xv = *(const LAS u32x4*)(L_X + q * 144 + (32 * m + 8 * fq) * 2); float xf8[8]; unpack8(xv, xf8);
; #pragma unroll
;                       for (int e = 0; e < 8; ++e) y[e] += dskip * xf8[e]; }
;                   *(u32x4*)(yrow + 32 * m) = pack8(y); } }
.LBB0_123:
	s_or_b64 exec, exec, s[0:1]
	v_cndmask_b32_e64 v72, v170, v89, s[12:13]
	v_cndmask_b32_e64 v76, v169, v90, s[12:13]
	v_cndmask_b32_e64 v80, v168, v91, s[12:13]
	v_cndmask_b32_e64 v72, v72, v81, s[14:15]
	v_cndmask_b32_e64 v76, v76, v82, s[14:15]
	v_cndmask_b32_e64 v80, v80, v83, s[14:15]
	v_cndmask_b32_e64 v72, v72, v93, s[16:17]
	v_cndmask_b32_e64 v76, v76, v94, s[16:17]
	v_cndmask_b32_e64 v80, v80, v95, s[16:17]
	v_cndmask_b32_e64 v72, v72, v85, s[18:19]
	v_cndmask_b32_e64 v76, v76, v86, s[18:19]
	v_cndmask_b32_e64 v80, v80, v87, s[18:19]
	v_cndmask_b32_e64 v72, v72, v77, s[20:21]
	v_cndmask_b32_e64 v76, v76, v78, s[20:21]
	v_cndmask_b32_e64 v77, v80, v79, s[20:21]
	v_sub_f32_e32 v78, v117, v181
	v_cndmask_b32_e64 v72, v72, v73, s[22:23]
	v_cndmask_b32_e64 v73, v76, v74, s[22:23]
	v_cndmask_b32_e64 v74, v77, v75, s[22:23]
	v_sub_f32_e32 v75, v117, v182
	v_mul_f32_e32 v78, 0x3fb8aa3b, v78
	v_mul_f32_e32 v75, 0x3fb8aa3b, v75
	v_sub_f32_e32 v76, v117, v183
	v_exp_f32_e32 v78, v78
	v_exp_f32_e32 v75, v75
	v_mul_f32_e32 v76, 0x3fb8aa3b, v76
	v_exp_f32_e32 v76, v76
	v_mul_f32_e32 v72, v72, v78
	v_mul_f32_e32 v73, v73, v75
	v_mul_f32_e32 v72, v185, v72
	v_mul_f32_e32 v73, v186, v73
	v_mul_f32_e32 v74, v74, v76
	v_cndmask_b32_e64 v72, 0, v72, s[62:63]
	v_cndmask_b32_e64 v73, 0, v73, s[64:65]
	v_mul_f32_e32 v74, v187, v74
	v_cndmask_b32_e64 v74, 0, v74, s[66:67]
	v_cvt_pk_bf16_f32 v72, v172, v72
	v_cvt_pk_bf16_f32 v73, v73, v74
	ds_write_b64 v155, v[72:73]
	ds_read_b128 v[72:75], v156
	ds_read_b64_tr_b16 v[76:77], v157
	ds_read_b64_tr_b16 v[78:79], v157 offset:576
	ds_read_b64_tr_b16 v[80:81], v157 offset:8
	ds_read_b64_tr_b16 v[84:85], v157 offset:64
	ds_read_b64_tr_b16 v[88:89], v157 offset:72
	ds_read_b64_tr_b16 v[82:83], v157 offset:584
	ds_read_b64_tr_b16 v[86:87], v157 offset:640
	ds_read_b64_tr_b16 v[90:91], v157 offset:648
	s_waitcnt lgkmcnt(6)
	v_mfma_f32_16x16x32_bf16 v[76:79], v[76:79], v[72:75], 0
	s_waitcnt lgkmcnt(2)
	v_mfma_f32_16x16x32_bf16 v[80:83], v[80:83], v[72:75], 0
	s_waitcnt lgkmcnt(1)
	v_mfma_f32_16x16x32_bf16 v[84:87], v[84:87], v[72:75], 0
	s_waitcnt lgkmcnt(0)
	v_mfma_f32_16x16x32_bf16 v[72:75], v[88:91], v[72:75], 0
	ds_read_b128 v[88:91], v156 offset:64
	ds_read_b64_tr_b16 v[92:93], v157 offset:4608
	ds_read_b64_tr_b16 v[94:95], v157 offset:5184
	ds_read_b64_tr_b16 v[96:97], v157 offset:4616
	ds_read_b64_tr_b16 v[100:101], v157 offset:4672
	ds_read_b64_tr_b16 v[168:169], v157 offset:4680
	ds_read_b64_tr_b16 v[98:99], v157 offset:5192
	ds_read_b64_tr_b16 v[102:103], v157 offset:5248
	ds_read_b64_tr_b16 v[170:171], v157 offset:5256
	s_waitcnt lgkmcnt(6)
	v_mfma_f32_16x16x32_bf16 v[76:79], v[92:95], v[88:91], v[76:79]
	s_waitcnt lgkmcnt(2)
	v_mfma_f32_16x16x32_bf16 v[80:83], v[96:99], v[88:91], v[80:83]
	s_waitcnt lgkmcnt(0)
	v_mfma_f32_16x16x32_bf16 v[72:75], v[168:171], v[88:91], v[72:75]
	v_mfma_f32_16x16x32_bf16 v[84:87], v[100:103], v[88:91], v[84:87]
	ds_read_b128 v[88:91], v156 offset:128
	ds_read_b64_tr_b16 v[92:93], v157 offset:9216
	ds_read_b64_tr_b16 v[94:95], v157 offset:9792
	ds_read_b64_tr_b16 v[96:97], v157 offset:9224
	ds_read_b64_tr_b16 v[100:101], v157 offset:9280
	ds_read_b64_tr_b16 v[168:169], v157 offset:9288
	ds_read_b64_tr_b16 v[98:99], v157 offset:9800
	ds_read_b64_tr_b16 v[102:103], v157 offset:9856
	ds_read_b64_tr_b16 v[170:171], v157 offset:9864
	s_waitcnt lgkmcnt(6)
	v_mfma_f32_16x16x32_bf16 v[76:79], v[92:95], v[88:91], v[76:79]
	s_waitcnt lgkmcnt(2)
	v_mfma_f32_16x16x32_bf16 v[80:83], v[96:99], v[88:91], v[80:83]
	s_waitcnt lgkmcnt(0)
	v_mfma_f32_16x16x32_bf16 v[72:75], v[168:171], v[88:91], v[72:75]
	v_mfma_f32_16x16x32_bf16 v[84:87], v[100:103], v[88:91], v[84:87]
	ds_read_b128 v[88:91], v156 offset:192
	ds_read_b64_tr_b16 v[92:93], v157 offset:13824
	ds_read_b64_tr_b16 v[94:95], v157 offset:14400
	ds_read_b64_tr_b16 v[96:97], v157 offset:13832
	ds_read_b64_tr_b16 v[100:101], v157 offset:13888
	ds_read_b64_tr_b16 v[168:169], v157 offset:13896
	ds_read_b64_tr_b16 v[98:99], v157 offset:14408
	ds_read_b64_tr_b16 v[102:103], v157 offset:14464
	ds_read_b64_tr_b16 v[170:171], v157 offset:14472
	s_waitcnt lgkmcnt(6)
	v_mfma_f32_16x16x32_bf16 v[92:95], v[92:95], v[88:91], v[76:79]
	s_waitcnt lgkmcnt(1)
	v_mfma_f32_16x16x32_bf16 v[76:79], v[100:103], v[88:91], v[84:87]
	s_waitcnt lgkmcnt(0)
	v_mfma_f32_16x16x32_bf16 v[72:75], v[168:171], v[88:91], v[72:75]
	v_mfma_f32_16x16x32_bf16 v[96:99], v[96:99], v[88:91], v[80:83]
	s_nop 2
	v_fma_f32 v80, v68, v116, v92
	v_fma_f32 v81, v69, v116, v93
	s_nop 2
	v_pk_fma_f32 v[68:69], v[64:65], v[116:117], v[96:97] op_sel_hi:[1,0,1]
	v_cndmask_b32_e64 v64, 0, 1, s[42:43]
	v_pk_fma_f32 v[70:71], v[70:71], v[116:117], v[94:95] op_sel_hi:[1,0,1]
	v_cmp_ne_u32_e64 s[0:1], 1, v64
	s_andn2_b64 vcc, exec, s[42:43]
	v_pk_fma_f32 v[66:67], v[66:67], v[116:117], v[98:99] op_sel_hi:[1,0,1]
	s_cbranch_vccnz .LBB0_125
	ds_read_b128 v[82:85], v165
	s_waitcnt lgkmcnt(0)
	v_lshlrev_b32_e32 v64, 16, v82
	v_and_b32_e32 v65, 0xffff0000, v82
	v_pk_fma_f32 v[80:81], v[110:111], v[64:65], v[80:81]
	v_lshlrev_b32_e32 v64, 16, v83
	v_and_b32_e32 v65, 0xffff0000, v83
	v_pk_fma_f32 v[70:71], v[110:111], v[64:65], v[70:71]
	v_lshlrev_b32_e32 v64, 16, v84
	v_and_b32_e32 v65, 0xffff0000, v84
	v_pk_fma_f32 v[68:69], v[110:111], v[64:65], v[68:69]
	v_lshlrev_b32_e32 v64, 16, v85
	v_and_b32_e32 v65, 0xffff0000, v85
	v_pk_fma_f32 v[66:67], v[110:111], v[64:65], v[66:67]

; __device__ __forceinline__ void gemm_phase(const int tid, LAS unsigned char* lds, const Gemm g, const StaticOrder& S, const int mode  , void* Cout, const int ldc, float* rvs, const float* rbs, const float* rbs_tail) {
;     ...
;         { const float* rp = cur.kc >= 0 ? rbs_tail : rbs;
;           if (rp != nullptr) {
; #pragma unroll
;             for (int ai = 0; ai < 2; ++ai)
; #pragma unroll
;                 for (int m = 0; m < 4; ++m) { const float rb = rsqrtf(rp[cur.pm * BM + ai * HALF + wr * 64 + m * 16 + fr] * (1.f / 2048.f) + EPS);
; #pragma unroll
;                     for (int bj = 0; bj < 2; ++bj)
; #pragma unroll
;                         for (int n = 0; n < 2; ++n) acc[ai][bj][m][n] = acc[ai][bj][m][n] * rb; } } }
.LBB0_234:
	s_and_b64 s[24:25], s[24:25], exec
	s_cselect_b32 s25, s9, s11
	s_cselect_b32 s24, s8, s10
	s_cmp_eq_u64 s[24:25], 0
	v_lshl_add_u32 v142, s58, 8, v146
	v_readlane_b32 s68, v254, 53
	s_cbranch_scc1 .LBB0_236
	v_ashrrev_i32_e32 v143, 31, v142
	v_lshl_add_u64 v[144:145], v[142:143], 2, s[24:25]
	global_load_dword v168, v[144:145], off
	global_load_dword v169, v[144:145], off offset:64
	global_load_dword v170, v[144:145], off offset:128
	global_load_dword v171, v[144:145], off offset:192
	global_load_dword v172, v[144:145], off offset:512
	global_load_dword v173, v[144:145], off offset:576
	global_load_dword v174, v[144:145], off offset:640
	global_load_dword v175, v[144:145], off offset:704
	s_mov_b32 s2, 0x800000
	s_waitcnt vmcnt(7)
	v_fmamk_f32 v143, v168, 0x3a000000, v197
	v_cmp_gt_f32_e32 vcc, s2, v143
	v_mul_f32_e32 v150, 0x4b800000, v143
	s_nop 0
	v_cndmask_b32_e32 v143, v143, v150, vcc
	v_rsq_f32_e32 v143, v143
	s_nop 0
	v_mul_f32_e32 v150, 0x45800000, v143
	v_cndmask_b32_e32 v150, v143, v150, vcc
	v_pk_mul_f32 v[126:127], v[126:127], v[150:151] op_sel_hi:[1,0]
	v_pk_mul_f32 v[124:125], v[124:125], v[150:151] op_sel_hi:[1,0]
	v_pk_mul_f32 v[122:123], v[122:123], v[150:151] op_sel_hi:[1,0]
	v_pk_mul_f32 v[120:121], v[120:121], v[150:151] op_sel_hi:[1,0]
	v_pk_mul_f32 v[110:111], v[110:111], v[150:151] op_sel_hi:[1,0]
	v_pk_mul_f32 v[108:109], v[108:109], v[150:151] op_sel_hi:[1,0]
	v_pk_mul_f32 v[102:103], v[102:103], v[150:151] op_sel_hi:[1,0]
	v_pk_mul_f32 v[100:101], v[100:101], v[150:151] op_sel_hi:[1,0]
	s_waitcnt vmcnt(6)
	v_fmamk_f32 v143, v169, 0x3a000000, v197
	v_cmp_gt_f32_e32 vcc, s2, v143
	v_mul_f32_e32 v150, 0x4b800000, v143
	s_nop 0
	v_cndmask_b32_e32 v143, v143, v150, vcc
	v_rsq_f32_e32 v143, v143
	s_nop 0
	v_mul_f32_e32 v150, 0x45800000, v143
	v_cndmask_b32_e32 v150, v143, v150, vcc
	v_pk_mul_f32 v[118:119], v[118:119], v[150:151] op_sel_hi:[1,0]
	v_pk_mul_f32 v[116:117], v[116:117], v[150:151] op_sel_hi:[1,0]
	v_pk_mul_f32 v[114:115], v[114:115], v[150:151] op_sel_hi:[1,0]
	v_pk_mul_f32 v[112:113], v[112:113], v[150:151] op_sel_hi:[1,0]
	v_pk_mul_f32 v[94:95], v[94:95], v[150:151] op_sel_hi:[1,0]
	v_pk_mul_f32 v[92:93], v[92:93], v[150:151] op_sel_hi:[1,0]
	v_pk_mul_f32 v[86:87], v[86:87], v[150:151] op_sel_hi:[1,0]
	v_pk_mul_f32 v[84:85], v[84:85], v[150:151] op_sel_hi:[1,0]
	s_waitcnt vmcnt(5)
	v_fmamk_f32 v143, v170, 0x3a000000, v197
	v_cmp_gt_f32_e32 vcc, s2, v143
	v_mul_f32_e32 v150, 0x4b800000, v143
	s_nop 0
	v_cndmask_b32_e32 v143, v143, v150, vcc
	v_rsq_f32_e32 v143, v143
	s_nop 0
	v_mul_f32_e32 v150, 0x45800000, v143
	v_cndmask_b32_e32 v150, v143, v150, vcc
	v_pk_mul_f32 v[106:107], v[106:107], v[150:151] op_sel_hi:[1,0]
	v_pk_mul_f32 v[104:105], v[104:105], v[150:151] op_sel_hi:[1,0]
	v_pk_mul_f32 v[98:99], v[98:99], v[150:151] op_sel_hi:[1,0]
	v_pk_mul_f32 v[96:97], v[96:97], v[150:151] op_sel_hi:[1,0]
	v_pk_mul_f32 v[78:79], v[78:79], v[150:151] op_sel_hi:[1,0]
	v_pk_mul_f32 v[76:77], v[76:77], v[150:151] op_sel_hi:[1,0]
	v_pk_mul_f32 v[74:75], v[74:75], v[150:151] op_sel_hi:[1,0]
	v_pk_mul_f32 v[72:73], v[72:73], v[150:151] op_sel_hi:[1,0]
	s_waitcnt vmcnt(4)
	v_fmamk_f32 v143, v171, 0x3a000000, v197
	v_cmp_gt_f32_e32 vcc, s2, v143
	v_mul_f32_e32 v150, 0x4b800000, v143
	s_nop 0
	v_cndmask_b32_e32 v143, v143, v150, vcc
	v_rsq_f32_e32 v143, v143
	s_nop 0
	v_mul_f32_e32 v150, 0x45800000, v143
	v_cndmask_b32_e32 v150, v143, v150, vcc
	v_pk_mul_f32 v[90:91], v[90:91], v[150:151] op_sel_hi:[1,0]
	v_pk_mul_f32 v[88:89], v[88:89], v[150:151] op_sel_hi:[1,0]
	v_pk_mul_f32 v[82:83], v[82:83], v[150:151] op_sel_hi:[1,0]
	v_pk_mul_f32 v[80:81], v[80:81], v[150:151] op_sel_hi:[1,0]
	v_pk_mul_f32 v[70:71], v[70:71], v[150:151] op_sel_hi:[1,0]
	v_pk_mul_f32 v[68:69], v[68:69], v[150:151] op_sel_hi:[1,0]
	v_pk_mul_f32 v[66:67], v[66:67], v[150:151] op_sel_hi:[1,0]
	v_pk_mul_f32 v[64:65], v[64:65], v[150:151] op_sel_hi:[1,0]
	s_waitcnt vmcnt(3)
	v_fmamk_f32 v143, v172, 0x3a000000, v197
	v_cmp_gt_f32_e32 vcc, s2, v143
	v_mul_f32_e32 v150, 0x4b800000, v143
	s_nop 0
	v_cndmask_b32_e32 v143, v143, v150, vcc
	v_rsq_f32_e32 v143, v143
	s_nop 0
	v_mul_f32_e32 v150, 0x45800000, v143
	v_cndmask_b32_e32 v150, v143, v150, vcc
	v_pk_mul_f32 v[62:63], v[62:63], v[150:151] op_sel_hi:[1,0]
	v_pk_mul_f32 v[60:61], v[60:61], v[150:151] op_sel_hi:[1,0]
	v_pk_mul_f32 v[58:59], v[58:59], v[150:151] op_sel_hi:[1,0]
	v_pk_mul_f32 v[56:57], v[56:57], v[150:151] op_sel_hi:[1,0]
	v_pk_mul_f32 v[46:47], v[46:47], v[150:151] op_sel_hi:[1,0]
	v_pk_mul_f32 v[44:45], v[44:45], v[150:151] op_sel_hi:[1,0]
	v_pk_mul_f32 v[42:43], v[42:43], v[150:151] op_sel_hi:[1,0]
	v_pk_mul_f32 v[40:41], v[40:41], v[150:151] op_sel_hi:[1,0]
	s_waitcnt vmcnt(2)
	v_fmamk_f32 v143, v173, 0x3a000000, v197
	v_cmp_gt_f32_e32 vcc, s2, v143
	v_mul_f32_e32 v150, 0x4b800000, v143
	s_nop 0
	v_cndmask_b32_e32 v143, v143, v150, vcc
	v_rsq_f32_e32 v143, v143
	s_nop 0
	v_mul_f32_e32 v150, 0x45800000, v143
	v_cndmask_b32_e32 v150, v143, v150, vcc
	v_pk_mul_f32 v[54:55], v[54:55], v[150:151] op_sel_hi:[1,0]
	v_pk_mul_f32 v[52:53], v[52:53], v[150:151] op_sel_hi:[1,0]
	v_pk_mul_f32 v[50:51], v[50:51], v[150:151] op_sel_hi:[1,0]
	v_pk_mul_f32 v[48:49], v[48:49], v[150:151] op_sel_hi:[1,0]
	v_pk_mul_f32 v[30:31], v[30:31], v[150:151] op_sel_hi:[1,0]
	v_pk_mul_f32 v[28:29], v[28:29], v[150:151] op_sel_hi:[1,0]
	v_pk_mul_f32 v[26:27], v[26:27], v[150:151] op_sel_hi:[1,0]
	v_pk_mul_f32 v[24:25], v[24:25], v[150:151] op_sel_hi:[1,0]
	s_waitcnt vmcnt(1)
	v_fmamk_f32 v143, v174, 0x3a000000, v197
	v_cmp_gt_f32_e32 vcc, s2, v143
	v_mul_f32_e32 v150, 0x4b800000, v143
	s_nop 0
	v_cndmask_b32_e32 v143, v143, v150, vcc
	v_rsq_f32_e32 v143, v143
	s_nop 0
	v_mul_f32_e32 v150, 0x45800000, v143
	v_cndmask_b32_e32 v150, v143, v150, vcc
	v_pk_mul_f32 v[38:39], v[38:39], v[150:151] op_sel_hi:[1,0]
	v_pk_mul_f32 v[36:37], v[36:37], v[150:151] op_sel_hi:[1,0]
	v_pk_mul_f32 v[34:35], v[34:35], v[150:151] op_sel_hi:[1,0]
	v_pk_mul_f32 v[32:33], v[32:33], v[150:151] op_sel_hi:[1,0]
	v_pk_mul_f32 v[14:15], v[14:15], v[150:151] op_sel_hi:[1,0]
	v_pk_mul_f32 v[12:13], v[12:13], v[150:151] op_sel_hi:[1,0]
	v_pk_mul_f32 v[10:11], v[10:11], v[150:151] op_sel_hi:[1,0]
	v_pk_mul_f32 v[8:9], v[8:9], v[150:151] op_sel_hi:[1,0]
	s_waitcnt vmcnt(0)
	v_fmamk_f32 v143, v175, 0x3a000000, v197
	v_cmp_gt_f32_e32 vcc, s2, v143
	v_mul_f32_e32 v144, 0x4b800000, v143
	s_nop 0
	v_cndmask_b32_e32 v143, v143, v144, vcc
	v_rsq_f32_e32 v143, v143
	s_nop 0
	v_mul_f32_e32 v144, 0x45800000, v143
	v_cndmask_b32_e32 v144, v143, v144, vcc
	v_pk_mul_f32 v[22:23], v[22:23], v[144:145] op_sel_hi:[1,0]
	v_pk_mul_f32 v[20:21], v[20:21], v[144:145] op_sel_hi:[1,0]
	v_pk_mul_f32 v[18:19], v[18:19], v[144:145] op_sel_hi:[1,0]
	v_pk_mul_f32 v[16:17], v[16:17], v[144:145] op_sel_hi:[1,0]
	v_pk_mul_f32 v[6:7], v[6:7], v[144:145] op_sel_hi:[1,0]
	v_pk_mul_f32 v[4:5], v[4:5], v[144:145] op_sel_hi:[1,0]
	v_pk_mul_f32 v[2:3], v[2:3], v[144:145] op_sel_hi:[1,0]
	v_pk_mul_f32 v[0:1], v[0:1], v[144:145] op_sel_hi:[1,0]
